# weight conversion: contiguous block of tiles per WG instead of stride-nb round robin (v12 + edit_cvt_block)
# baseline (speedup 1.0000x reference)
.LBB0_17:
	s_sub_i32 s26, s68, s37
	s_ashr_i32 s27, s26, 31
	s_abs_i32 s26, s26
	s_mul_hi_u32 s28, s26, s33
	s_mul_i32 s28, s28, s31
	s_sub_i32 s26, s26, s28
	s_sub_i32 s28, s26, s31
	s_cmp_ge_u32 s26, s31
	s_cselect_b32 s26, s28, s26
	s_sub_i32 s28, s26, s31
	s_cmp_ge_u32 s26, s31
	s_cselect_b32 s26, s28, s26
	v_cvt_f32_u32_e32 v1, s39
	s_xor_b32 s26, s26, s27
	s_sub_i32 s26, s26, s27
	s_load_dwordx2 s[24:25], s[24:25], 0x0
	s_ashr_i32 s27, s26, 31
	s_and_b32 s27, s27, s69
	v_rcp_iflag_f32_e32 v1, v1
	s_mul_i32 s23, s39, s2
	s_add_i32 s40, s27, s26
	s_add_i32 s98, s23, s31
	s_add_i32 s98, s98, -1
	s_mul_hi_u32 s99, s98, s33
	s_mul_i32 s100, s99, s31
	s_sub_i32 s98, s98, s100
	s_sub_i32 s100, s98, s31
	s_cmp_ge_u32 s98, s31
	s_cselect_b32 s98, s100, s98
	s_cselect_b32 s100, 1, 0
	s_add_i32 s99, s99, s100
	s_cmp_ge_u32 s98, s31
	s_cselect_b32 s100, 1, 0
	s_add_i32 s99, s99, s100
	s_mul_i32 s40, s40, s99
	s_add_i32 s99, s40, s99
	s_min_i32 s99, s99, s23
	s_cmp_lt_i32 s40, s99
	s_cselect_b64 s[26:27], -1, 0
	s_cmp_ge_i32 s40, s99
	s_cbranch_scc1 .LBB0_21
	v_mul_f32_e32 v2, 0x4f7ffffe, v1
	v_cvt_u32_f32_e32 v2, v2
	s_sub_i32 s41, 0, s39
	s_abs_i32 s29, s40
	s_ashr_i32 s28, s40, 31
	v_readfirstlane_b32 s42, v2
	s_mul_i32 s41, s41, s42
	s_mul_hi_u32 s41, s42, s41
	s_add_i32 s42, s42, s41
	s_mul_hi_u32 s41, s29, s42
	s_mul_i32 s42, s41, s39
	s_sub_i32 s29, s29, s42
	s_add_i32 s42, s41, 1
	s_sub_i32 s43, s29, s39
	s_cmp_ge_u32 s29, s39
	s_cselect_b32 s41, s42, s41
	s_cselect_b32 s29, s43, s29
	s_add_i32 s42, s41, 1
	s_cmp_ge_u32 s29, s39
	s_cselect_b32 s29, s42, s41
	s_xor_b32 s29, s29, s28
	s_sub_i32 s41, s29, s28
	s_mul_i32 s28, s41, s39
	s_sub_i32 s28, s40, s28
	v_mov_b32_e32 v18, v212
	s_lshl_b32 s28, s28, 6
	s_waitcnt vmcnt(1)
	v_mov_b32_e32 v4, v3
	v_lshlrev_b32_e32 v2, 2, v18
	v_and_or_b32 v19, v2, 60, s28
	v_cmp_gt_i32_e32 vcc, s35, v19
	s_or_b64 vcc, s[20:21], vcc
	s_addk_i32 s28, 0xcf80
	s_cmpk_lt_u32 s28, 0x1800
	v_mov_b32_e32 v5, v3
	v_mov_b32_e32 v6, v3
	v_mov_b32_e32 v7, v3
	s_waitcnt vmcnt(0)
	v_mov_b32_e32 v8, v3
	v_mov_b32_e32 v9, v3
	s_cselect_b64 s[28:29], -1, 0
	v_mov_b32_e32 v2, v3
	v_mov_b64_e32 v[10:11], v[8:9]
	s_or_b64 s[42:43], vcc, s[28:29]
	v_mov_b64_e32 v[8:9], v[6:7]
	v_mov_b64_e32 v[6:7], v[4:5]
	v_mov_b64_e32 v[4:5], v[2:3]
	s_and_saveexec_b64 s[28:29], s[42:43]
	s_cbranch_execz .LBB0_20
	v_subrev_u32_e32 v2, 48, v19
	s_lshl_b32 s41, s41, 6
	v_cndmask_b32_e32 v4, v2, v19, vcc
	v_ashrrev_i32_e32 v2, 4, v18
	v_add_u32_e32 v2, s41, v2
	v_mad_i64_i32 v[6:7], s[42:43], s22, v2, 0
	v_add_u32_e32 v2, 0x200, v18
	v_ashrrev_i32_e32 v2, 4, v2
	v_add_u32_e32 v2, s41, v2
	v_ashrrev_i32_e32 v5, 31, v4
	v_mad_i64_i32 v[8:9], s[42:43], s22, v2, 0
	s_waitcnt lgkmcnt(0)
	v_lshl_add_u64 v[6:7], v[6:7], 2, s[24:25]
	v_lshlrev_b64 v[4:5], 2, v[4:5]
	v_lshl_add_u64 v[8:9], v[8:9], 2, s[24:25]
	v_lshl_add_u64 v[6:7], v[6:7], 0, v[4:5]
	v_lshl_add_u64 v[8:9], v[8:9], 0, v[4:5]
	global_load_dwordx4 v[4:7], v[6:7], off
	s_nop 0
	global_load_dwordx4 v[8:11], v[8:9], off

.LBB0_21:
	s_andn2_b64 vcc, exec, s[26:27]
	s_cbranch_vccnz .LBB0_8
	v_mul_f32_e32 v1, 0x4f7ffffe, v1
	v_cvt_u32_f32_e32 v1, v1
	s_sub_i32 s26, 0, s39
	s_lshl_b32 s41, s39, 6
	s_lshl_b32 s46, s40, 6
	v_readfirstlane_b32 s27, v1
	s_mul_i32 s26, s26, s27
	s_mul_hi_u32 s26, s27, s26
	s_add_i32 s42, s27, s26
	s_movk_i32 s43, 0x40
	s_sub_i32 s44, 0, s41
.LBB0_23:
	v_mov_b32_e32 v1, v212
	s_add_i32 s45, s40, 1
	v_lshlrev_b32_e32 v2, 4, v1
	v_and_b32_e32 v2, 0xf0, v2
	v_add_u32_e32 v2, 0, v2
	v_ashrrev_i32_e32 v18, 4, v1
	v_add_u32_e32 v1, 0x200, v1
	v_mad_u64_u32 v[18:19], s[26:27], v18, s36, v[2:3]
	v_ashrrev_i32_e32 v1, 4, v1
	s_waitcnt vmcnt(1)
	ds_write2_b32 v18, v4, v5 offset1:1
	ds_write2_b32 v18, v6, v7 offset0:2 offset1:3
	v_mad_u64_u32 v[18:19], s[26:27], v1, s36, v[2:3]
	s_cmp_ge_i32 s45, s99
	s_cselect_b64 s[26:27], -1, 0
	s_cmp_lt_i32 s45, s99
	s_mov_b64 s[28:29], -1
	s_waitcnt vmcnt(0)
	ds_write2_b32 v18, v8, v9 offset1:1
	ds_write2_b32 v18, v10, v11 offset0:2 offset1:3
	s_waitcnt lgkmcnt(0)
	s_barrier
	s_cbranch_scc1 .LBB0_25
	s_add_i32 s47, s46, s43
	s_mov_b64 s[28:29], 0

.LBB0_199:
	v_readlane_b32 s20, v238, 62
	s_add_i32 s20, s20, s26
	s_sub_i32 s20, s68, s20
	s_ashr_i32 s21, s20, 31
	s_abs_i32 s20, s20
	v_readlane_b32 s22, v237, 2
	s_mul_hi_u32 s22, s20, s22
	v_readlane_b32 s23, v237, 1
	s_mul_i32 s22, s22, s23
	s_sub_i32 s20, s20, s22
	s_sub_i32 s22, s20, s23
	s_cmp_ge_u32 s20, s23
	s_cselect_b32 s20, s22, s20
	s_sub_i32 s22, s20, s23
	s_cmp_ge_u32 s20, s23
	s_cselect_b32 s20, s22, s20
	v_cvt_f32_u32_e32 v0, s31
	s_xor_b32 s20, s20, s21
	s_sub_i32 s20, s20, s21
	s_ashr_i32 s21, s20, 31
	s_and_b32 s21, s21, s51
	v_rcp_iflag_f32_e32 v10, v0
	s_mul_i32 s15, s31, s30
	s_add_i32 s35, s21, s20
	v_readlane_b32 s101, v237, 2
	s_add_i32 s98, s15, s51
	s_add_i32 s98, s98, -1
	s_mul_hi_u32 s99, s98, s101
	s_mul_i32 s100, s99, s51
	s_sub_i32 s98, s98, s100
	s_sub_i32 s100, s98, s51
	s_cmp_ge_u32 s98, s51
	s_cselect_b32 s98, s100, s98
	s_cselect_b32 s100, 1, 0
	s_add_i32 s99, s99, s100
	s_cmp_ge_u32 s98, s51
	s_cselect_b32 s100, 1, 0
	s_add_i32 s99, s99, s100
	s_mul_i32 s35, s35, s99
	s_add_i32 s99, s35, s99
	s_min_i32 s99, s99, s15
	s_cmp_lt_i32 s35, s99
	s_cselect_b64 s[20:21], -1, 0
	s_cmp_ge_i32 s35, s99
	s_cbranch_scc0 .LBB0_201
	s_andn2_b64 vcc, exec, s[20:21]
	s_cbranch_vccnz .LBB0_190
	s_branch .LBB0_204

.LBB0_204:
	v_mul_f32_e32 v0, 0x4f7ffffe, v10
	v_cvt_u32_f32_e32 v0, v0
	s_sub_i32 s20, 0, s31
	s_lshl_b32 s34, s31, 6
	s_lshl_b32 s40, s35, 6
	v_readfirstlane_b32 s21, v0
	s_mul_i32 s20, s20, s21
	s_mul_hi_u32 s20, s21, s20
	s_add_i32 s36, s21, s20
	s_movk_i32 s37, 0x40
	s_sub_i32 s38, 0, s34
.LBB0_205:
	v_mov_b32_e32 v12, v212
	s_add_i32 s39, s35, 1
	v_lshlrev_b32_e32 v0, 4, v12
	v_and_b32_e32 v0, 0xf0, v0
	v_add_u32_e32 v0, 0, v0
	v_ashrrev_i32_e32 v10, 4, v12
	v_mad_u64_u32 v[10:11], s[20:21], v10, s48, v[0:1]
	s_waitcnt vmcnt(1)
	ds_write2_b32 v10, v2, v3 offset1:1
	ds_write2_b32 v10, v4, v5 offset0:2 offset1:3
	v_add_u32_e32 v10, 0x200, v12
	v_ashrrev_i32_e32 v10, 4, v10
	v_mad_u64_u32 v[10:11], s[20:21], v10, s48, v[0:1]
	s_cmp_ge_i32 s39, s99
	s_cselect_b64 s[20:21], -1, 0
	s_cmp_lt_i32 s39, s99
	s_mov_b64 s[22:23], -1
	s_waitcnt vmcnt(0)
	ds_write2_b32 v10, v6, v7 offset1:1
	ds_write2_b32 v10, v8, v9 offset0:2 offset1:3
	s_waitcnt lgkmcnt(0)
	s_barrier
	s_cbranch_scc1 .LBB0_207
	s_add_i32 s41, s40, s37
	s_mov_b64 s[22:23], 0
